# scan phase: blocks 256..351 (co-resident with the gdn_k2/ml_k2 chain blocks) take no sample task; 1024 sample tasks spread over the other 320 blocks
# speedup vs baseline: 1.0332x; 1.0106x over previous
.LBB0_415:
	s_andn2_b64 vcc, exec, s[0:1]
	s_cbranch_vccnz .LBB0_474
	s_cmpk_lt_i32 s52, 0x60
	s_mov_b64 s[0:1], -1
	s_cbranch_scc1 .LBB0_462
	s_cmpk_gt_u32 s52, 0x45f
	s_cbranch_scc1 .LBB0_461
	v_readlane_b32 s0, v239, 53
	s_lshl_b32 s51, s0, 7
	s_sub_u32 s50, s52, 0x100
	s_cmp_lt_u32 s50, 0x60
	s_cbranch_scc1 .LBB0_461
	s_cmp_lt_u32 s52, 0x100
	s_cselect_b32 s50, 0, 0x60
	s_sub_u32 s57, s52, s50
	s_movk_i32 s50, 0x140
	s_add_i32 s54, s57, 0xfffffda0
	s_add_i32 s55, s57, 0xffffffa0
	s_mov_b32 s56, s57
	s_branch .LBB0_421
